# v31 + nt on the attention output stores (consumed ~1.3 ms later)
# baseline (speedup 1.0000x reference)
; __device__ __forceinline__ int crow(int r, int hi) { return (r & 3) + 8 * (r >> 2) + 4 * hi; }
; __device__ __forceinline__ unsigned cvtpk(float lo, float hi) { unsigned r; asm volatile("v_cvt_pk_bf16_f32 %0, %1, %2" : "=v"(r) : "v"(lo), "v"(hi)); return r; }
; __device__ __forceinline__ void attn_unit(const bf16_t* __restrict__ Qb, const bf16_t* __restrict__ Kh, const bf16_t* __restrict__ Vh, bf16_t* __restrict__ Ob, int seq, char* lds, const float* rope, int qpos0) {
;     ...
;   if (hi == 0) li_l[r32] = l_reg; asm volatile("s_waitcnt lgkmcnt(0)" ::: "memory");
;   float rli[16];
; #pragma unroll
;   for (int r = 0; r < 16; ++r) rli[r] = __builtin_amdgcn_rcpf(li_l[crow(r, hi)]);
;   bf16_t* Ow = Ob + (long)(wid * QBLK) * LDO;
; #pragma unroll
;   for (int r = 0; r < 16; ++r) { int orow = crow(r, hi);
; #pragma unroll
;     for (int d0 = 0; d0 < 2; ++d0) { const float val = o[d0][r] * rli[r]; Ow[(long)orow * LDO + d0 * 32 + r32] = (bf16_t)(cvtpk(val, val) & 0xffffu); } }
;   __builtin_amdgcn_s_setprio(0);
.LBB0_653:
	s_or_b64 exec, exec, s[4:5]
	s_waitcnt lgkmcnt(0)
	v_add_u32_e32 v40, v119, v116
	ds_read_b128 v[32:35], v40
	ds_read_b128 v[36:39], v40 offset:32
	s_lshl_b64 s[4:5], s[12:13], 11
	s_add_u32 s4, s33, s4
	v_ashrrev_i32_e32 v119, 31, v118
	s_waitcnt lgkmcnt(1)
	v_rcp_f32_e32 v41, v32
	v_rcp_f32_e32 v42, v33
	v_rcp_f32_e32 v43, v34
	v_rcp_f32_e32 v44, v35
	ds_read_b128 v[32:35], v40 offset:64
	s_addc_u32 s5, s72, s5
	s_waitcnt lgkmcnt(1)
	v_rcp_f32_e32 v45, v36
	v_rcp_f32_e32 v46, v37
	v_rcp_f32_e32 v47, v38
	v_rcp_f32_e32 v48, v39
	ds_read_b128 v[36:39], v40 offset:96
	s_waitcnt lgkmcnt(1)
	v_rcp_f32_e32 v40, v32
	v_rcp_f32_e32 v49, v33
	v_lshlrev_b64 v[32:33], 11, v[118:119]
	v_lshl_add_u64 v[32:33], s[4:5], 0, v[32:33]
	v_lshlrev_b32_e32 v116, 1, v138
	v_rcp_f32_e32 v50, v34
	v_rcp_f32_e32 v51, v35
	v_lshlrev_b32_e32 v34, 13, v139
	v_lshl_add_u64 v[32:33], v[32:33], 0, v[116:117]
	v_mov_b32_e32 v35, v117
	v_mul_f32_e32 v0, v0, v41
	v_lshl_add_u64 v[32:33], v[32:33], 0, v[34:35]
	v_cvt_pk_bf16_f32 v0, v0, v0
	global_store_short v[32:33], v0, off nt
	v_mul_f32_e32 v0, v16, v41
	v_cvt_pk_bf16_f32 v0, v0, v0
	global_store_short v[32:33], v0, off offset:64 nt
	v_mul_f32_e32 v0, v1, v42
	v_cvt_pk_bf16_f32 v0, v0, v0
	global_store_short v[32:33], v0, off offset:2048 nt
	v_mul_f32_e32 v0, v17, v42
	v_cvt_pk_bf16_f32 v0, v0, v0
	global_store_short v[32:33], v0, off offset:2112 nt
	v_mul_f32_e32 v0, v2, v43
	s_movk_i32 s4, 0x1000
	v_cvt_pk_bf16_f32 v2, v0, v0
	v_add_co_u32_e32 v0, vcc, s4, v32
	s_movk_i32 s4, 0x4000
	s_nop 0
	v_addc_co_u32_e32 v1, vcc, 0, v33, vcc
	global_store_short v[0:1], v2, off nt
	v_mul_f32_e32 v2, v18, v43
	v_cvt_pk_bf16_f32 v2, v2, v2
	global_store_short v[0:1], v2, off offset:64 nt
	v_mul_f32_e32 v2, v3, v44
	v_cvt_pk_bf16_f32 v2, v2, v2
	global_store_short v[0:1], v2, off offset:2048 nt
	v_mul_f32_e32 v2, v19, v44
	v_cvt_pk_bf16_f32 v2, v2, v2
	global_store_short v[0:1], v2, off offset:2112 nt
	v_mul_f32_e32 v0, v4, v45
	v_cvt_pk_bf16_f32 v4, v0, v0
	v_add_co_u32_e32 v0, vcc, s4, v32
	s_movk_i32 s4, 0x5000
	s_nop 0
	v_addc_co_u32_e32 v1, vcc, 0, v33, vcc
	v_add_co_u32_e32 v2, vcc, s4, v32
	s_mov_b32 s4, 0x8000
	s_nop 0
	v_addc_co_u32_e32 v3, vcc, 0, v33, vcc
	global_store_short v[2:3], v4, off offset:-4096 nt
	v_mul_f32_e32 v4, v20, v45
	v_cvt_pk_bf16_f32 v4, v4, v4
	global_store_short v[0:1], v4, off offset:64 nt
	v_mul_f32_e32 v4, v5, v46
	v_cvt_pk_bf16_f32 v4, v4, v4
	global_store_short v[0:1], v4, off offset:2048 nt
	v_mul_f32_e32 v4, v21, v46
	v_cvt_pk_bf16_f32 v4, v4, v4
	global_store_short v[0:1], v4, off offset:2112 nt
	v_mul_f32_e32 v0, v6, v47
	v_cvt_pk_bf16_f32 v0, v0, v0
	global_store_short v[2:3], v0, off nt
	v_mul_f32_e32 v0, v22, v47
	v_cvt_pk_bf16_f32 v0, v0, v0
	global_store_short v[2:3], v0, off offset:64 nt
	v_mul_f32_e32 v0, v7, v48
	v_cvt_pk_bf16_f32 v0, v0, v0
	global_store_short v[2:3], v0, off offset:2048 nt
	v_mul_f32_e32 v0, v23, v48
	v_cvt_pk_bf16_f32 v0, v0, v0
	global_store_short v[2:3], v0, off offset:2112 nt
	v_mul_f32_e32 v0, v8, v40
	v_cvt_pk_bf16_f32 v4, v0, v0
	v_add_co_u32_e32 v0, vcc, s4, v32
	s_mov_b32 s4, 0x9000
	s_nop 0
	v_addc_co_u32_e32 v1, vcc, 0, v33, vcc
	v_add_co_u32_e32 v2, vcc, s4, v32
	s_waitcnt lgkmcnt(0)
	v_rcp_f32_e32 v36, v36
	v_addc_co_u32_e32 v3, vcc, 0, v33, vcc
	global_store_short v[2:3], v4, off offset:-4096 nt
	v_mul_f32_e32 v4, v24, v40
	v_cvt_pk_bf16_f32 v4, v4, v4
	global_store_short v[0:1], v4, off offset:64 nt
	v_mul_f32_e32 v4, v9, v49
	v_cvt_pk_bf16_f32 v4, v4, v4
	global_store_short v[0:1], v4, off offset:2048 nt
	v_mul_f32_e32 v4, v25, v49
	v_cvt_pk_bf16_f32 v4, v4, v4
	global_store_short v[0:1], v4, off offset:2112 nt
	v_mul_f32_e32 v0, v10, v50
	v_cvt_pk_bf16_f32 v0, v0, v0
	global_store_short v[2:3], v0, off nt
	v_mul_f32_e32 v0, v26, v50
	v_cvt_pk_bf16_f32 v0, v0, v0
	global_store_short v[2:3], v0, off offset:64 nt
	v_mul_f32_e32 v0, v11, v51
	v_cvt_pk_bf16_f32 v0, v0, v0
	global_store_short v[2:3], v0, off offset:2048 nt
	v_mul_f32_e32 v0, v27, v51
	v_cvt_pk_bf16_f32 v0, v0, v0
	global_store_short v[2:3], v0, off offset:2112 nt
	v_mul_f32_e32 v0, v12, v36
	s_mov_b32 s4, 0xc000
	v_cvt_pk_bf16_f32 v4, v0, v0
	v_add_co_u32_e32 v0, vcc, s4, v32
	s_mov_b32 s4, 0xd000
	s_nop 0
	v_addc_co_u32_e32 v1, vcc, 0, v33, vcc
	v_rcp_f32_e32 v37, v37
	v_add_co_u32_e32 v2, vcc, s4, v32
	v_rcp_f32_e32 v38, v38
	s_nop 0
	v_addc_co_u32_e32 v3, vcc, 0, v33, vcc
	global_store_short v[2:3], v4, off offset:-4096 nt
	v_mul_f32_e32 v4, v28, v36
	v_cvt_pk_bf16_f32 v4, v4, v4
	global_store_short v[0:1], v4, off offset:64 nt
	v_mul_f32_e32 v4, v13, v37
	v_cvt_pk_bf16_f32 v4, v4, v4
	global_store_short v[0:1], v4, off offset:2048 nt
	v_mul_f32_e32 v4, v29, v37
	v_rcp_f32_e32 v39, v39
	v_cvt_pk_bf16_f32 v4, v4, v4
	global_store_short v[0:1], v4, off offset:2112 nt
	v_mul_f32_e32 v0, v14, v38
	v_cvt_pk_bf16_f32 v0, v0, v0
	global_store_short v[2:3], v0, off nt
	v_mul_f32_e32 v0, v30, v38
	v_cvt_pk_bf16_f32 v0, v0, v0
	global_store_short v[2:3], v0, off offset:64 nt
	v_mul_f32_e32 v0, v15, v39
	v_cvt_pk_bf16_f32 v0, v0, v0
	global_store_short v[2:3], v0, off offset:2048 nt
	v_mul_f32_e32 v0, v31, v39
	v_cvt_pk_bf16_f32 v0, v0, v0
	global_store_short v[2:3], v0, off offset:2112 nt
	s_setprio 0
	s_movk_i32 s6, 0x2000
	s_andn2_b64 vcc, exec, s[16:17]
	s_mov_b64 s[4:5], 0
	s_barrier
	s_cbranch_vccz .LBB0_699

; __device__ __forceinline__ int crow(int r, int hi) { return (r & 3) + 8 * (r >> 2) + 4 * hi; }
; __device__ __forceinline__ unsigned cvtpk(float lo, float hi) { unsigned r; asm volatile("v_cvt_pk_bf16_f32 %0, %1, %2" : "=v"(r) : "v"(lo), "v"(hi)); return r; }
; __device__ __forceinline__ void attn_unit(const bf16_t* __restrict__ Qb, const bf16_t* __restrict__ Kh, const bf16_t* __restrict__ Vh, bf16_t* __restrict__ Ob, int seq, char* lds, const float* rope, int qpos0) {
;     ...
;   if (hi == 0) li_l[r32] = l_reg; asm volatile("s_waitcnt lgkmcnt(0)" ::: "memory");
;   float rli[16];
; #pragma unroll
;   for (int r = 0; r < 16; ++r) rli[r] = __builtin_amdgcn_rcpf(li_l[crow(r, hi)]);
;   bf16_t* Ow = Ob + (long)(wid * QBLK) * LDO;
; #pragma unroll
;   for (int r = 0; r < 16; ++r) { int orow = crow(r, hi);
; #pragma unroll
;     for (int d0 = 0; d0 < 2; ++d0) { const float val = o[d0][r] * rli[r]; Ow[(long)orow * LDO + d0 * 32 + r32] = (bf16_t)(cvtpk(val, val) & 0xffffu); } }
;   __builtin_amdgcn_s_setprio(0);
.LBB0_700:
	s_or_b64 exec, exec, s[4:5]
	s_waitcnt lgkmcnt(0)
	v_add_u32_e32 v40, v119, v116
	ds_read_b128 v[32:35], v40
	ds_read_b128 v[36:39], v40 offset:32
	s_lshl_b32 s0, s0, 1
	s_add_u32 s4, s73, s0
	v_ashrrev_i32_e32 v119, 31, v118
	s_waitcnt lgkmcnt(1)
	v_rcp_f32_e32 v41, v32
	v_rcp_f32_e32 v42, v33
	v_rcp_f32_e32 v43, v34
	v_rcp_f32_e32 v44, v35
	ds_read_b128 v[32:35], v40 offset:64
	s_addc_u32 s5, s74, 0
	s_waitcnt lgkmcnt(1)
	v_rcp_f32_e32 v45, v36
	v_rcp_f32_e32 v46, v37
	v_rcp_f32_e32 v47, v38
	v_rcp_f32_e32 v48, v39
	ds_read_b128 v[36:39], v40 offset:96
	s_waitcnt lgkmcnt(1)
	v_rcp_f32_e32 v40, v32
	v_rcp_f32_e32 v49, v33
	v_lshlrev_b64 v[32:33], 11, v[118:119]
	v_lshl_add_u64 v[32:33], s[4:5], 0, v[32:33]
	v_lshlrev_b32_e32 v116, 1, v138
	v_rcp_f32_e32 v50, v34
	v_rcp_f32_e32 v51, v35
	v_lshlrev_b32_e32 v34, 13, v139
	v_lshl_add_u64 v[32:33], v[32:33], 0, v[116:117]
	v_mov_b32_e32 v35, v117
	v_mul_f32_e32 v0, v0, v41
	v_lshl_add_u64 v[32:33], v[32:33], 0, v[34:35]
	v_cvt_pk_bf16_f32 v0, v0, v0
	global_store_short v[32:33], v0, off nt
	v_mul_f32_e32 v0, v16, v41
	v_cvt_pk_bf16_f32 v0, v0, v0
	global_store_short v[32:33], v0, off offset:64 nt
	v_mul_f32_e32 v0, v1, v42
	v_cvt_pk_bf16_f32 v0, v0, v0
	global_store_short v[32:33], v0, off offset:2048 nt
	v_mul_f32_e32 v0, v17, v42
	v_cvt_pk_bf16_f32 v0, v0, v0
	global_store_short v[32:33], v0, off offset:2112 nt
	v_mul_f32_e32 v0, v2, v43
	s_movk_i32 s0, 0x1000
	v_cvt_pk_bf16_f32 v2, v0, v0
	v_add_co_u32_e32 v0, vcc, s0, v32
	s_movk_i32 s0, 0x4000
	s_nop 0
	v_addc_co_u32_e32 v1, vcc, 0, v33, vcc
	global_store_short v[0:1], v2, off nt
	v_mul_f32_e32 v2, v18, v43
	v_cvt_pk_bf16_f32 v2, v2, v2
	global_store_short v[0:1], v2, off offset:64 nt
	v_mul_f32_e32 v2, v3, v44
	v_cvt_pk_bf16_f32 v2, v2, v2
	global_store_short v[0:1], v2, off offset:2048 nt
	v_mul_f32_e32 v2, v19, v44
	v_cvt_pk_bf16_f32 v2, v2, v2
	global_store_short v[0:1], v2, off offset:2112 nt
	v_mul_f32_e32 v0, v4, v45
	v_cvt_pk_bf16_f32 v4, v0, v0
	v_add_co_u32_e32 v0, vcc, s0, v32
	s_movk_i32 s0, 0x5000
	s_nop 0
	v_addc_co_u32_e32 v1, vcc, 0, v33, vcc
	v_add_co_u32_e32 v2, vcc, s0, v32
	s_mov_b32 s0, 0x8000
	s_nop 0
	v_addc_co_u32_e32 v3, vcc, 0, v33, vcc
	global_store_short v[2:3], v4, off offset:-4096 nt
	v_mul_f32_e32 v4, v20, v45
	v_cvt_pk_bf16_f32 v4, v4, v4
	global_store_short v[0:1], v4, off offset:64 nt
	v_mul_f32_e32 v4, v5, v46
	v_cvt_pk_bf16_f32 v4, v4, v4
	global_store_short v[0:1], v4, off offset:2048 nt
	v_mul_f32_e32 v4, v21, v46
	v_cvt_pk_bf16_f32 v4, v4, v4
	global_store_short v[0:1], v4, off offset:2112 nt
	v_mul_f32_e32 v0, v6, v47
	v_cvt_pk_bf16_f32 v0, v0, v0
	global_store_short v[2:3], v0, off nt
	v_mul_f32_e32 v0, v22, v47
	v_cvt_pk_bf16_f32 v0, v0, v0
	global_store_short v[2:3], v0, off offset:64 nt
	v_mul_f32_e32 v0, v7, v48
	v_cvt_pk_bf16_f32 v0, v0, v0
	global_store_short v[2:3], v0, off offset:2048 nt
	v_mul_f32_e32 v0, v23, v48
	v_cvt_pk_bf16_f32 v0, v0, v0
	global_store_short v[2:3], v0, off offset:2112 nt
	v_mul_f32_e32 v0, v8, v40
	v_cvt_pk_bf16_f32 v4, v0, v0
	v_add_co_u32_e32 v0, vcc, s0, v32
	s_mov_b32 s0, 0x9000
	s_nop 0
	v_addc_co_u32_e32 v1, vcc, 0, v33, vcc
	v_add_co_u32_e32 v2, vcc, s0, v32
	s_waitcnt lgkmcnt(0)
	v_rcp_f32_e32 v36, v36
	v_addc_co_u32_e32 v3, vcc, 0, v33, vcc
	global_store_short v[2:3], v4, off offset:-4096 nt
	v_mul_f32_e32 v4, v24, v40
	v_cvt_pk_bf16_f32 v4, v4, v4
	global_store_short v[0:1], v4, off offset:64 nt
	v_mul_f32_e32 v4, v9, v49
	v_cvt_pk_bf16_f32 v4, v4, v4
	global_store_short v[0:1], v4, off offset:2048 nt
	v_mul_f32_e32 v4, v25, v49
	v_cvt_pk_bf16_f32 v4, v4, v4
	global_store_short v[0:1], v4, off offset:2112 nt
	v_mul_f32_e32 v0, v10, v50
	v_cvt_pk_bf16_f32 v0, v0, v0
	global_store_short v[2:3], v0, off nt
	v_mul_f32_e32 v0, v26, v50
	v_cvt_pk_bf16_f32 v0, v0, v0
	global_store_short v[2:3], v0, off offset:64 nt
	v_mul_f32_e32 v0, v11, v51
	v_cvt_pk_bf16_f32 v0, v0, v0
	global_store_short v[2:3], v0, off offset:2048 nt
	v_mul_f32_e32 v0, v27, v51
	v_cvt_pk_bf16_f32 v0, v0, v0
	global_store_short v[2:3], v0, off offset:2112 nt
	v_mul_f32_e32 v0, v12, v36
	s_mov_b32 s0, 0xc000
	v_cvt_pk_bf16_f32 v4, v0, v0
	v_add_co_u32_e32 v0, vcc, s0, v32
	s_mov_b32 s0, 0xd000
	s_nop 0
	v_addc_co_u32_e32 v1, vcc, 0, v33, vcc
	v_rcp_f32_e32 v37, v37
	v_add_co_u32_e32 v2, vcc, s0, v32
	v_rcp_f32_e32 v38, v38
	s_nop 0
	v_addc_co_u32_e32 v3, vcc, 0, v33, vcc
	global_store_short v[2:3], v4, off offset:-4096 nt
	v_mul_f32_e32 v4, v28, v36
	v_cvt_pk_bf16_f32 v4, v4, v4
	global_store_short v[0:1], v4, off offset:64 nt
	v_mul_f32_e32 v4, v13, v37
	v_cvt_pk_bf16_f32 v4, v4, v4
	global_store_short v[0:1], v4, off offset:2048 nt
	v_mul_f32_e32 v4, v29, v37
	v_rcp_f32_e32 v39, v39
	v_cvt_pk_bf16_f32 v4, v4, v4
	global_store_short v[0:1], v4, off offset:2112 nt
	v_mul_f32_e32 v0, v14, v38
	v_cvt_pk_bf16_f32 v0, v0, v0
	global_store_short v[2:3], v0, off nt
	v_mul_f32_e32 v0, v30, v38
	v_cvt_pk_bf16_f32 v0, v0, v0
	global_store_short v[2:3], v0, off offset:64 nt
	v_mul_f32_e32 v0, v15, v39
	v_cvt_pk_bf16_f32 v0, v0, v0
	global_store_short v[2:3], v0, off offset:2048 nt
	v_mul_f32_e32 v0, v31, v39
	v_cvt_pk_bf16_f32 v0, v0, v0
	global_store_short v[2:3], v0, off offset:2112 nt
	s_setprio 0
	s_add_i32 s79, s79, 1
	s_cmp_eq_u32 s79, 4
	s_barrier
	s_cbranch_scc1 .LBB0_746
